# X3 RMS-norm reduction: 16 serial ds_bpermute butterflies replaced by interleaved DPP adds + one batched bpermute step; 4-byte pad keeps downstream code phase
# speedup vs baseline: 1.0194x; 1.0043x over previous
; DI int crow(int i, int h) { return (i & 3) + 8 * (i >> 2) + 4 * h; }
; DI void mlstm_x3(const Params& p, LAS unsigned char* lds, int item, int tid_in, int lane_in, int wave) {
;     ...
; #pragma unroll
;     for (int i = 0; i < 16; ++i) { float q = hs[0][i] * hs[0][i] + hs[1][i] * hs[1][i];
; #pragma unroll
;         for (int o = 1; o < 32; o <<= 1) q += __int_as_float(__builtin_amdgcn_ds_bpermute((lane ^ o) << 2, __float_as_int(q)));
;         if (r_ == 0) s_ssq[(32 * ti + crow(i, h)) * 2 + eh] = q; }
.LBB0_794:
	v_cmp_ne_u32_e32 vcc, 0, v173
	v_cmp_eq_u32_e64 s[38:39], 0, v173
	v_xor_b32_e32 v6, 64, v190
	v_pk_mul_f32 v[64:65], v[160:161], v[160:161]
	v_pk_mul_f32 v[66:67], v[156:157], v[156:157]
	v_pk_mul_f32 v[68:69], v[152:153], v[152:153]
	v_pk_mul_f32 v[70:71], v[148:149], v[148:149]
	v_pk_mul_f32 v[72:73], v[144:145], v[144:145]
	v_pk_mul_f32 v[74:75], v[140:141], v[140:141]
	v_pk_mul_f32 v[76:77], v[136:137], v[136:137]
	v_pk_mul_f32 v[78:79], v[128:129], v[128:129]
	v_pk_fma_f32 v[64:65], v[158:159], v[158:159], v[64:65]
	v_pk_fma_f32 v[66:67], v[154:155], v[154:155], v[66:67]
	v_pk_fma_f32 v[68:69], v[150:151], v[150:151], v[68:69]
	v_pk_fma_f32 v[70:71], v[146:147], v[146:147], v[70:71]
	v_pk_fma_f32 v[72:73], v[142:143], v[142:143], v[72:73]
	v_pk_fma_f32 v[74:75], v[138:139], v[138:139], v[74:75]
	v_pk_fma_f32 v[76:77], v[134:135], v[134:135], v[76:77]
	v_pk_fma_f32 v[78:79], v[130:131], v[130:131], v[78:79]
	s_nop 1
	v_add_f32_dpp v64, v64, v64 quad_perm:[1,0,3,2] row_mask:0xf bank_mask:0xf
	v_add_f32_dpp v65, v65, v65 quad_perm:[1,0,3,2] row_mask:0xf bank_mask:0xf
	v_add_f32_dpp v66, v66, v66 quad_perm:[1,0,3,2] row_mask:0xf bank_mask:0xf
	v_add_f32_dpp v67, v67, v67 quad_perm:[1,0,3,2] row_mask:0xf bank_mask:0xf
	v_add_f32_dpp v68, v68, v68 quad_perm:[1,0,3,2] row_mask:0xf bank_mask:0xf
	v_add_f32_dpp v69, v69, v69 quad_perm:[1,0,3,2] row_mask:0xf bank_mask:0xf
	v_add_f32_dpp v70, v70, v70 quad_perm:[1,0,3,2] row_mask:0xf bank_mask:0xf
	v_add_f32_dpp v71, v71, v71 quad_perm:[1,0,3,2] row_mask:0xf bank_mask:0xf
	v_add_f32_dpp v72, v72, v72 quad_perm:[1,0,3,2] row_mask:0xf bank_mask:0xf
	v_add_f32_dpp v73, v73, v73 quad_perm:[1,0,3,2] row_mask:0xf bank_mask:0xf
	v_add_f32_dpp v74, v74, v74 quad_perm:[1,0,3,2] row_mask:0xf bank_mask:0xf
	v_add_f32_dpp v75, v75, v75 quad_perm:[1,0,3,2] row_mask:0xf bank_mask:0xf
	v_add_f32_dpp v76, v76, v76 quad_perm:[1,0,3,2] row_mask:0xf bank_mask:0xf
	v_add_f32_dpp v77, v77, v77 quad_perm:[1,0,3,2] row_mask:0xf bank_mask:0xf
	v_add_f32_dpp v78, v78, v78 quad_perm:[1,0,3,2] row_mask:0xf bank_mask:0xf
	v_add_f32_dpp v79, v79, v79 quad_perm:[1,0,3,2] row_mask:0xf bank_mask:0xf
	v_add_f32_dpp v64, v64, v64 quad_perm:[2,3,0,1] row_mask:0xf bank_mask:0xf
	v_add_f32_dpp v65, v65, v65 quad_perm:[2,3,0,1] row_mask:0xf bank_mask:0xf
	v_add_f32_dpp v66, v66, v66 quad_perm:[2,3,0,1] row_mask:0xf bank_mask:0xf
	v_add_f32_dpp v67, v67, v67 quad_perm:[2,3,0,1] row_mask:0xf bank_mask:0xf
	v_add_f32_dpp v68, v68, v68 quad_perm:[2,3,0,1] row_mask:0xf bank_mask:0xf
	v_add_f32_dpp v69, v69, v69 quad_perm:[2,3,0,1] row_mask:0xf bank_mask:0xf
	v_add_f32_dpp v70, v70, v70 quad_perm:[2,3,0,1] row_mask:0xf bank_mask:0xf
	v_add_f32_dpp v71, v71, v71 quad_perm:[2,3,0,1] row_mask:0xf bank_mask:0xf
	v_add_f32_dpp v72, v72, v72 quad_perm:[2,3,0,1] row_mask:0xf bank_mask:0xf
	v_add_f32_dpp v73, v73, v73 quad_perm:[2,3,0,1] row_mask:0xf bank_mask:0xf
	v_add_f32_dpp v74, v74, v74 quad_perm:[2,3,0,1] row_mask:0xf bank_mask:0xf
	v_add_f32_dpp v75, v75, v75 quad_perm:[2,3,0,1] row_mask:0xf bank_mask:0xf
	v_add_f32_dpp v76, v76, v76 quad_perm:[2,3,0,1] row_mask:0xf bank_mask:0xf
	v_add_f32_dpp v77, v77, v77 quad_perm:[2,3,0,1] row_mask:0xf bank_mask:0xf
	v_add_f32_dpp v78, v78, v78 quad_perm:[2,3,0,1] row_mask:0xf bank_mask:0xf
	v_add_f32_dpp v79, v79, v79 quad_perm:[2,3,0,1] row_mask:0xf bank_mask:0xf
	v_add_f32_dpp v64, v64, v64 row_half_mirror row_mask:0xf bank_mask:0xf
	v_add_f32_dpp v65, v65, v65 row_half_mirror row_mask:0xf bank_mask:0xf
	v_add_f32_dpp v66, v66, v66 row_half_mirror row_mask:0xf bank_mask:0xf
	v_add_f32_dpp v67, v67, v67 row_half_mirror row_mask:0xf bank_mask:0xf
	v_add_f32_dpp v68, v68, v68 row_half_mirror row_mask:0xf bank_mask:0xf
	v_add_f32_dpp v69, v69, v69 row_half_mirror row_mask:0xf bank_mask:0xf
	v_add_f32_dpp v70, v70, v70 row_half_mirror row_mask:0xf bank_mask:0xf
	v_add_f32_dpp v71, v71, v71 row_half_mirror row_mask:0xf bank_mask:0xf
	v_add_f32_dpp v72, v72, v72 row_half_mirror row_mask:0xf bank_mask:0xf
	v_add_f32_dpp v73, v73, v73 row_half_mirror row_mask:0xf bank_mask:0xf
	v_add_f32_dpp v74, v74, v74 row_half_mirror row_mask:0xf bank_mask:0xf
	v_add_f32_dpp v75, v75, v75 row_half_mirror row_mask:0xf bank_mask:0xf
	v_add_f32_dpp v76, v76, v76 row_half_mirror row_mask:0xf bank_mask:0xf
	v_add_f32_dpp v77, v77, v77 row_half_mirror row_mask:0xf bank_mask:0xf
	v_add_f32_dpp v78, v78, v78 row_half_mirror row_mask:0xf bank_mask:0xf
	v_add_f32_dpp v79, v79, v79 row_half_mirror row_mask:0xf bank_mask:0xf
	v_add_f32_dpp v64, v64, v64 row_mirror row_mask:0xf bank_mask:0xf
	v_add_f32_dpp v65, v65, v65 row_mirror row_mask:0xf bank_mask:0xf
	v_add_f32_dpp v66, v66, v66 row_mirror row_mask:0xf bank_mask:0xf
	v_add_f32_dpp v67, v67, v67 row_mirror row_mask:0xf bank_mask:0xf
	v_add_f32_dpp v68, v68, v68 row_mirror row_mask:0xf bank_mask:0xf
	v_add_f32_dpp v69, v69, v69 row_mirror row_mask:0xf bank_mask:0xf
	v_add_f32_dpp v70, v70, v70 row_mirror row_mask:0xf bank_mask:0xf
	v_add_f32_dpp v71, v71, v71 row_mirror row_mask:0xf bank_mask:0xf
	v_add_f32_dpp v72, v72, v72 row_mirror row_mask:0xf bank_mask:0xf
	v_add_f32_dpp v73, v73, v73 row_mirror row_mask:0xf bank_mask:0xf
	v_add_f32_dpp v74, v74, v74 row_mirror row_mask:0xf bank_mask:0xf
	v_add_f32_dpp v75, v75, v75 row_mirror row_mask:0xf bank_mask:0xf
	v_add_f32_dpp v76, v76, v76 row_mirror row_mask:0xf bank_mask:0xf
	v_add_f32_dpp v77, v77, v77 row_mirror row_mask:0xf bank_mask:0xf
	v_add_f32_dpp v78, v78, v78 row_mirror row_mask:0xf bank_mask:0xf
	v_add_f32_dpp v79, v79, v79 row_mirror row_mask:0xf bank_mask:0xf
	s_nop 1
	ds_bpermute_b32 v80, v6, v64
	ds_bpermute_b32 v81, v6, v65
	ds_bpermute_b32 v82, v6, v66
	ds_bpermute_b32 v83, v6, v67
	ds_bpermute_b32 v84, v6, v68
	ds_bpermute_b32 v85, v6, v69
	ds_bpermute_b32 v86, v6, v70
	ds_bpermute_b32 v87, v6, v71
	ds_bpermute_b32 v88, v6, v72
	ds_bpermute_b32 v89, v6, v73
	ds_bpermute_b32 v90, v6, v74
	ds_bpermute_b32 v91, v6, v75
	ds_bpermute_b32 v92, v6, v76
	ds_bpermute_b32 v93, v6, v77
	ds_bpermute_b32 v94, v6, v78
	ds_bpermute_b32 v95, v6, v79
	v_lshlrev_b32_e32 v0, 3, v189
	v_lshl_add_u32 v96, v188, 3, s69
	v_lshl_add_u32 v97, v187, 3, s69
	v_lshl_add_u32 v98, v186, 3, s69
	v_lshl_add_u32 v99, v185, 3, s69
	v_lshl_add_u32 v100, v184, 3, s69
	v_lshl_add_u32 v101, v183, 3, s69
	v_lshl_add_u32 v102, v182, 3, s69
	v_lshl_add_u32 v103, v181, 3, s69
	v_lshl_add_u32 v104, v180, 3, s69
	v_lshl_add_u32 v105, v179, 3, s69
	v_lshl_add_u32 v106, v178, 3, s69
	v_lshl_add_u32 v107, v177, 3, s69
	v_lshl_add_u32 v108, v176, 3, s69
	v_lshl_add_u32 v109, v175, 3, s69
	v_lshl_add_u32 v110, v174, 3, s69
	v_add_u32_e32 v111, s69, v0
	s_and_saveexec_b64 s[4:5], s[38:39]
	s_waitcnt lgkmcnt(15)
; DI int crow(int i, int h) { return (i & 3) + 8 * (i >> 2) + 4 * h; }
; DI void mlstm_x3(const Params& p, LAS unsigned char* lds, int item, int tid_in, int lane_in, int wave) {
;     ...
; #pragma unroll
;     for (int i = 0; i < 16; ++i) { float q = hs[0][i] * hs[0][i] + hs[1][i] * hs[1][i];
; #pragma unroll
;         for (int o = 1; o < 32; o <<= 1) q += __int_as_float(__builtin_amdgcn_ds_bpermute((lane ^ o) << 2, __float_as_int(q)));
;         if (r_ == 0) s_ssq[(32 * ti + crow(i, h)) * 2 + eh] = q; }
	v_add_f32_e32 v64, v64, v80
	ds_write_b32 v96, v64
	s_waitcnt lgkmcnt(14)
	v_add_f32_e32 v65, v65, v81
	ds_write_b32 v97, v65
	s_waitcnt lgkmcnt(13)
	v_add_f32_e32 v66, v66, v82
	ds_write_b32 v98, v66
	s_waitcnt lgkmcnt(12)
	v_add_f32_e32 v67, v67, v83
	ds_write_b32 v99, v67
	s_waitcnt lgkmcnt(11)
	v_add_f32_e32 v68, v68, v84
	ds_write_b32 v100, v68
	s_waitcnt lgkmcnt(10)
	v_add_f32_e32 v69, v69, v85
	ds_write_b32 v101, v69
	s_waitcnt lgkmcnt(9)
	v_add_f32_e32 v70, v70, v86
	ds_write_b32 v102, v70
	s_waitcnt lgkmcnt(8)
	v_add_f32_e32 v71, v71, v87
	ds_write_b32 v103, v71
	s_waitcnt lgkmcnt(7)
	v_add_f32_e32 v72, v72, v88
	ds_write_b32 v104, v72
	s_waitcnt lgkmcnt(6)
	v_add_f32_e32 v73, v73, v89
	ds_write_b32 v105, v73
	s_waitcnt lgkmcnt(5)
	v_add_f32_e32 v74, v74, v90
	ds_write_b32 v106, v74
	s_waitcnt lgkmcnt(4)
	v_add_f32_e32 v75, v75, v91
	ds_write_b32 v107, v75
	s_waitcnt lgkmcnt(3)
	v_add_f32_e32 v76, v76, v92
	ds_write_b32 v108, v76
	s_waitcnt lgkmcnt(2)
	v_add_f32_e32 v77, v77, v93
	ds_write_b32 v109, v77
	s_waitcnt lgkmcnt(1)
	v_add_f32_e32 v78, v78, v94
	ds_write_b32 v110, v78
	s_waitcnt lgkmcnt(0)
	v_add_f32_e32 v79, v79, v95
	ds_write_b32 v111, v79
	s_nop 0
	s_branch .LBB0_686
